# hoists the loop-invariant B-fragment LDS read base adds out of the GEMM main loop (uses VGPRs freed by SGPR-base DMA addressing)
# baseline (speedup 1.0000x reference)
; #define PG8_STAGE(bufoff, gbase, voff) do { _Pragma("unroll") for (int _i = 0; _i < 2; ++_i) \
;         __builtin_amdgcn_global_load_lds((const unsigned*)((const char*)(gbase) + (voff)[_i]), (LAS unsigned*)(lds + (bufoff) + ldsw + _i * 8192), 16, 0, 0); } while (0)
; #define PG8_LDA(dst, b, h) do { _Pragma("unroll") for (int m = 0; m < 4; ++m) _Pragma("unroll") for (int k = 0; k < 2; ++k) dst[m][k] = *(const LAS bf16x8*)(lds + PG8_SA(b, h) + aoff + m * 2048 + k * 1024); } while (0)
; #define PG8_LDB(dst, b, h) do { _Pragma("unroll") for (int n = 0; n < 2; ++n) _Pragma("unroll") for (int k = 0; k < 2; ++k) dst[n][k] = *(const LAS bf16x8*)(lds + PG8_SB(b, h) + boff + n * 2048 + k * 1024); } while (0)
; #define PG8_SCHED __builtin_amdgcn_sched_barrier(0)
; __device__ __forceinline__ void gemm_phase(LAS unsigned char* lds, const Gemm g, const StaticOrder& S, const Epi& E) {
;     ...
;         for (int t = 0; t < nt; t += 2) {
;             const bool last = (t == nt - 2);
;             const char* a1 = cA + (size_t)(t + 1) * kstep;
;             const char* a2 = last ? nA : cA + (size_t)(t + 2) * kstep; const char* b2 = last ? nB : cB + (size_t)(t + 2) * kstep;
;             const char* a3 = a2 + kstep; const char* b3 = b2 + kstep;
;             PG8_LDB(B0, 0, 0); PG8_LDB(B1, 0, 1); PG8_SCHED; PG8_LDA(At, 0, 0); PG8_STAGE(PG8_SA(1, 1), a1 + hstepA, voffA);
;     ...
;         for (int a = 0; a < 2; ++a)
; #pragma unroll
;             for (int b = 0; b < 2; ++b)
; #pragma unroll
;                 for (int m = 0; m < 4; ++m)
; #pragma unroll
;                     for (int n = 0; n < 2; ++n) acc[a][b][m][n] = (f32x4){0.f, 0.f, 0.f, 0.f};
;         cur = nxt; cA = nA; cB = nB; ++ui;
.LBB0_176:
	s_add_u32 s0, s0, 0x80
	s_addc_u32 s1, s1, 0
	s_add_u32 s5, s2, 0x100
	v_mov_b32_e32 v2, 0
	s_addc_u32 s16, s3, 0
	v_mov_b32_e32 v3, v2
	v_mov_b32_e32 v4, v2
	v_mov_b32_e32 v5, v2
	v_mov_b32_e32 v10, v2
	v_mov_b32_e32 v11, v2
	v_mov_b32_e32 v12, v2
	v_mov_b32_e32 v13, v2
	v_mov_b32_e32 v18, v2
	v_mov_b32_e32 v19, v2
	v_mov_b32_e32 v20, v2
	v_mov_b32_e32 v21, v2
	v_mov_b32_e32 v26, v2
	v_mov_b32_e32 v27, v2
	v_mov_b32_e32 v28, v2
	v_mov_b32_e32 v29, v2
	v_mov_b32_e32 v34, v2
	v_mov_b32_e32 v35, v2
	v_mov_b32_e32 v36, v2
	v_mov_b32_e32 v37, v2
	v_mov_b32_e32 v42, v2
	v_mov_b32_e32 v43, v2
	v_mov_b32_e32 v44, v2
	v_mov_b32_e32 v45, v2
	v_mov_b32_e32 v50, v2
	v_mov_b32_e32 v51, v2
	v_mov_b32_e32 v52, v2
	v_mov_b32_e32 v53, v2
	v_mov_b32_e32 v58, v2
	v_mov_b32_e32 v59, v2
	v_mov_b32_e32 v60, v2
	v_mov_b32_e32 v61, v2
	v_mov_b32_e32 v6, v2
	v_mov_b32_e32 v7, v2
	v_mov_b32_e32 v8, v2
	v_mov_b32_e32 v9, v2
	v_mov_b32_e32 v14, v2
	v_mov_b32_e32 v15, v2
	v_mov_b32_e32 v16, v2
	v_mov_b32_e32 v17, v2
	v_mov_b32_e32 v22, v2
	v_mov_b32_e32 v23, v2
	v_mov_b32_e32 v24, v2
	v_mov_b32_e32 v25, v2
	v_mov_b32_e32 v30, v2
	v_mov_b32_e32 v31, v2
	v_mov_b32_e32 v32, v2
	v_mov_b32_e32 v33, v2
	v_mov_b32_e32 v38, v2
	v_mov_b32_e32 v39, v2
	v_mov_b32_e32 v40, v2
	v_mov_b32_e32 v41, v2
	v_mov_b32_e32 v46, v2
	v_mov_b32_e32 v47, v2
	v_mov_b32_e32 v48, v2
	v_mov_b32_e32 v49, v2
	v_mov_b32_e32 v54, v2
	v_mov_b32_e32 v55, v2
	v_mov_b32_e32 v56, v2
	v_mov_b32_e32 v57, v2
	v_mov_b32_e32 v62, v2
	v_mov_b32_e32 v63, v2
	v_mov_b32_e32 v64, v2
	v_mov_b32_e32 v65, v2
	v_mov_b32_e32 v66, v2
	v_mov_b32_e32 v67, v2
	v_mov_b32_e32 v68, v2
	v_mov_b32_e32 v69, v2
	v_mov_b32_e32 v74, v2
	v_mov_b32_e32 v75, v2
	v_mov_b32_e32 v76, v2
	v_mov_b32_e32 v77, v2
	v_mov_b32_e32 v82, v2
	v_mov_b32_e32 v83, v2
	v_mov_b32_e32 v84, v2
	v_mov_b32_e32 v85, v2
	v_mov_b32_e32 v90, v2
	v_mov_b32_e32 v91, v2
	v_mov_b32_e32 v92, v2
	v_mov_b32_e32 v93, v2
	v_mov_b32_e32 v98, v2
	v_mov_b32_e32 v99, v2
	v_mov_b32_e32 v100, v2
	v_mov_b32_e32 v101, v2
	v_mov_b32_e32 v106, v2
	v_mov_b32_e32 v107, v2
	v_mov_b32_e32 v108, v2
	v_mov_b32_e32 v109, v2
	v_mov_b32_e32 v118, v2
	v_mov_b32_e32 v119, v2
	v_mov_b32_e32 v120, v2
	v_mov_b32_e32 v121, v2
	v_mov_b32_e32 v122, v2
	v_mov_b32_e32 v123, v2
	v_mov_b32_e32 v124, v2
	v_mov_b32_e32 v125, v2
	v_mov_b32_e32 v70, v2
	v_mov_b32_e32 v71, v2
	v_mov_b32_e32 v72, v2
	v_mov_b32_e32 v73, v2
	v_mov_b32_e32 v78, v2
	v_mov_b32_e32 v79, v2
	v_mov_b32_e32 v80, v2
	v_mov_b32_e32 v81, v2
	v_mov_b32_e32 v86, v2
	v_mov_b32_e32 v87, v2
	v_mov_b32_e32 v88, v2
	v_mov_b32_e32 v89, v2
	v_mov_b32_e32 v94, v2
	v_mov_b32_e32 v95, v2
	v_mov_b32_e32 v96, v2
	v_mov_b32_e32 v97, v2
	v_mov_b32_e32 v102, v2
	v_mov_b32_e32 v103, v2
	v_mov_b32_e32 v104, v2
	v_mov_b32_e32 v105, v2
	v_mov_b32_e32 v110, v2
	v_mov_b32_e32 v111, v2
	v_mov_b32_e32 v112, v2
	v_mov_b32_e32 v113, v2
	v_mov_b32_e32 v126, v2
	v_mov_b32_e32 v127, v2
	v_mov_b32_e32 v128, v2
	v_mov_b32_e32 v129, v2
	v_mov_b32_e32 v114, v2
	v_mov_b32_e32 v115, v2
	v_mov_b32_e32 v116, v2
	v_mov_b32_e32 v117, v2
	v_add_u32_e32 v226, s39, v177
	v_add_u32_e32 v227, s24, v177
	v_add_u32_e32 v228, s25, v177
	v_add_u32_e32 v229, s26, v177
.LBB0_177:
	s_waitcnt lgkmcnt(0)
	ds_read_b128 v[130:133], v226
	ds_read_b128 v[134:137], v226 offset:1024
	ds_read_b128 v[138:141], v226 offset:2048
	ds_read_b128 v[142:145], v226 offset:3072
	ds_read_b128 v[146:149], v227
	ds_read_b128 v[150:153], v227 offset:1024
	ds_read_b128 v[154:157], v227 offset:2048
	ds_read_b128 v[182:185], v227 offset:3072
	s_add_i32 s27, s17, 2
	s_add_u32 s2, s0, 0x80
	s_addc_u32 s3, s1, 0
	s_cmp_eq_u32 s85, s17
	s_cselect_b32 s3, s7, s3
	s_cselect_b32 s2, s6, s2
	s_cselect_b32 s41, s95, s16
	s_cselect_b32 s40, s94, s5
	s_add_i32 m0, s71, 0xc000
	ds_read_b128 v[186:189], v217
	ds_read_b128 v[190:193], v217 offset:1024
	ds_read_b128 v[194:197], v217 offset:2048
	ds_read_b128 v[198:201], v217 offset:3072
	ds_read_b128 v[202:205], v217 offset:4096
	ds_read_b128 v[206:209], v217 offset:5120
	ds_read_b128 v[218:221], v217 offset:6144
	ds_read_b128 v[222:225], v217 offset:7168
	global_load_lds_dwordx4 v178, s[0:1]
	s_add_i32 m0, s71, 0xe000
	s_nop 0
	global_load_lds_dwordx4 v180, s[0:1]
	s_waitcnt vmcnt(8)
	s_waitcnt lgkmcnt(0)
	s_barrier
	s_setprio 1
	v_mfma_f32_16x16x32_bf16 v[114:117], v[130:133], v[186:189], v[114:117]
	v_mfma_f32_16x16x32_bf16 v[126:129], v[138:141], v[186:189], v[126:129]
	v_mfma_f32_16x16x32_bf16 v[110:113], v[130:133], v[194:197], v[110:113]
	v_mfma_f32_16x16x32_bf16 v[102:105], v[138:141], v[194:197], v[102:105]
	v_mfma_f32_16x16x32_bf16 v[94:97], v[130:133], v[202:205], v[94:97]
	v_mfma_f32_16x16x32_bf16 v[86:89], v[138:141], v[202:205], v[86:89]
	v_mfma_f32_16x16x32_bf16 v[78:81], v[130:133], v[218:221], v[78:81]
	v_mfma_f32_16x16x32_bf16 v[70:73], v[138:141], v[218:221], v[70:73]
	v_mfma_f32_16x16x32_bf16 v[114:117], v[134:137], v[190:193], v[114:117]
	v_mfma_f32_16x16x32_bf16 v[126:129], v[142:145], v[190:193], v[126:129]
	v_mfma_f32_16x16x32_bf16 v[110:113], v[134:137], v[198:201], v[110:113]
	v_mfma_f32_16x16x32_bf16 v[102:105], v[142:145], v[198:201], v[102:105]
	v_mfma_f32_16x16x32_bf16 v[94:97], v[134:137], v[206:209], v[94:97]
	v_mfma_f32_16x16x32_bf16 v[86:89], v[142:145], v[206:209], v[86:89]
	v_mfma_f32_16x16x32_bf16 v[78:81], v[134:137], v[222:225], v[78:81]
	v_mfma_f32_16x16x32_bf16 v[70:73], v[142:145], v[222:225], v[70:73]
	v_mfma_f32_16x16x32_bf16 v[122:125], v[146:149], v[186:189], v[122:125]
	v_mfma_f32_16x16x32_bf16 v[118:121], v[154:157], v[186:189], v[118:121]
	v_mfma_f32_16x16x32_bf16 v[106:109], v[146:149], v[194:197], v[106:109]
	v_mfma_f32_16x16x32_bf16 v[98:101], v[154:157], v[194:197], v[98:101]
	v_mfma_f32_16x16x32_bf16 v[90:93], v[146:149], v[202:205], v[90:93]
	v_mfma_f32_16x16x32_bf16 v[82:85], v[154:157], v[202:205], v[82:85]
	v_mfma_f32_16x16x32_bf16 v[74:77], v[146:149], v[218:221], v[74:77]
	v_mfma_f32_16x16x32_bf16 v[66:69], v[154:157], v[218:221], v[66:69]
	v_mfma_f32_16x16x32_bf16 v[122:125], v[150:153], v[190:193], v[122:125]
	v_mfma_f32_16x16x32_bf16 v[118:121], v[182:185], v[190:193], v[118:121]
	v_mfma_f32_16x16x32_bf16 v[106:109], v[150:153], v[198:201], v[106:109]
	v_mfma_f32_16x16x32_bf16 v[98:101], v[182:185], v[198:201], v[98:101]
	v_mfma_f32_16x16x32_bf16 v[90:93], v[150:153], v[206:209], v[90:93]
	v_mfma_f32_16x16x32_bf16 v[82:85], v[182:185], v[206:209], v[82:85]
	v_mfma_f32_16x16x32_bf16 v[74:77], v[150:153], v[222:225], v[74:77]
	v_mfma_f32_16x16x32_bf16 v[66:69], v[182:185], v[222:225], v[66:69]
	s_setprio 0
	s_barrier
; #define PG8_STAGE(bufoff, gbase, voff) do { _Pragma("unroll") for (int _i = 0; _i < 2; ++_i) \
;         __builtin_amdgcn_global_load_lds((const unsigned*)((const char*)(gbase) + (voff)[_i]), (LAS unsigned*)(lds + (bufoff) + ldsw + _i * 8192), 16, 0, 0); } while (0)
; #define PG8_LDA(dst, b, h) do { _Pragma("unroll") for (int m = 0; m < 4; ++m) _Pragma("unroll") for (int k = 0; k < 2; ++k) dst[m][k] = *(const LAS bf16x8*)(lds + PG8_SA(b, h) + aoff + m * 2048 + k * 1024); } while (0)
; #define PG8_LDB(dst, b, h) do { _Pragma("unroll") for (int n = 0; n < 2; ++n) _Pragma("unroll") for (int k = 0; k < 2; ++k) dst[n][k] = *(const LAS bf16x8*)(lds + PG8_SB(b, h) + boff + n * 2048 + k * 1024); } while (0)
; #define PG8_MMA(ai, bj, At, Bt) do { __builtin_amdgcn_s_setprio(1); _Pragma("unroll") for (int m = 0; m < 4; ++m) _Pragma("unroll") for (int n = 0; n < 2; ++n) _Pragma("unroll") for (int k = 0; k < 2; ++k) \
;         acc[ai][bj][m][n] = __builtin_amdgcn_mfma_f32_16x16x32_bf16(Bt[n][k], At[m][k], acc[ai][bj][m][n], 0, 0, 0); __builtin_amdgcn_s_setprio(0); } while (0)
; #define PG8_WAIT_V(n) asm volatile("s_waitcnt vmcnt(" #n ")" ::: "memory")
; #define PG8_WAIT_L(n) asm volatile("s_waitcnt lgkmcnt(" #n ")" ::: "memory")
; #define PG8_BAR __builtin_amdgcn_s_barrier()
; #define PG8_SCHED __builtin_amdgcn_sched_barrier(0)
; __device__ __forceinline__ void gemm_phase(LAS unsigned char* lds, const Gemm g, const StaticOrder& S, const Epi& E) {
;     ...
;             PG8_WAIT_V(8); PG8_WAIT_L(0); PG8_BAR; PG8_MMA(0, 0, At, B0); PG8_MMA(0, 1, At, B1); PG8_BAR; PG8_SCHED;
;             PG8_LDA(At, 0, 1); PG8_STAGE(PG8_SB(0, 0), b2, voffB); PG8_STAGE(PG8_SB(0, 1), b2 + hstepB, voffB); PG8_STAGE(PG8_SA(0, 0), a2, voffA);
;             PG8_WAIT_V(8); PG8_WAIT_L(0); PG8_BAR; PG8_MMA(1, 0, At, B0); PG8_MMA(1, 1, At, B1); PG8_BAR; PG8_SCHED;
;             PG8_LDB(B0, 1, 0); PG8_LDB(B1, 1, 1); PG8_SCHED; PG8_LDA(At, 1, 0); PG8_STAGE(PG8_SA(0, 1), a2 + hstepA, voffA);
;             PG8_WAIT_V(8); PG8_WAIT_L(0); PG8_BAR; PG8_MMA(0, 0, At, B0); PG8_MMA(0, 1, At, B1); PG8_BAR; PG8_SCHED;
	s_add_i32 s17, s39, s70
	s_mov_b32 m0, s17
	ds_read_b128 v[186:189], v217 offset:16384
	ds_read_b128 v[190:193], v217 offset:17408
	ds_read_b128 v[194:197], v217 offset:18432
	ds_read_b128 v[198:201], v217 offset:19456
	ds_read_b128 v[202:205], v217 offset:20480
	ds_read_b128 v[206:209], v217 offset:21504
	ds_read_b128 v[218:221], v217 offset:22528
	ds_read_b128 v[222:225], v217 offset:23552
	global_load_lds_dwordx4 v160, s[40:41]
	s_add_i32 m0, s17, 0x2000
	s_add_i32 s17, s24, s70
	global_load_lds_dwordx4 v164, s[40:41]
	s_add_u32 s40, s40, s52
	s_addc_u32 s41, s41, s53
	s_mov_b32 m0, s17
	s_nop 0
	global_load_lds_dwordx4 v160, s[40:41]
	s_add_i32 m0, s17, 0x2000
	s_nop 0
	global_load_lds_dwordx4 v164, s[40:41]
	s_mov_b32 m0, s71
	s_nop 0
	global_load_lds_dwordx4 v158, s[2:3]
	s_mov_b32 m0, s34
	s_nop 0
	global_load_lds_dwordx4 v162, s[2:3]
	s_waitcnt vmcnt(8)
	s_waitcnt lgkmcnt(0)
	s_barrier
	s_setprio 1
	v_mfma_f32_16x16x32_bf16 v[62:65], v[130:133], v[186:189], v[62:65]
	v_mfma_f32_16x16x32_bf16 v[54:57], v[138:141], v[186:189], v[54:57]
	v_mfma_f32_16x16x32_bf16 v[46:49], v[130:133], v[194:197], v[46:49]
	v_mfma_f32_16x16x32_bf16 v[38:41], v[138:141], v[194:197], v[38:41]
	v_mfma_f32_16x16x32_bf16 v[30:33], v[130:133], v[202:205], v[30:33]
	v_mfma_f32_16x16x32_bf16 v[22:25], v[138:141], v[202:205], v[22:25]
	v_mfma_f32_16x16x32_bf16 v[14:17], v[130:133], v[218:221], v[14:17]
	v_mfma_f32_16x16x32_bf16 v[6:9], v[138:141], v[218:221], v[6:9]
	v_mfma_f32_16x16x32_bf16 v[62:65], v[134:137], v[190:193], v[62:65]
	v_mfma_f32_16x16x32_bf16 v[54:57], v[142:145], v[190:193], v[54:57]
	v_mfma_f32_16x16x32_bf16 v[46:49], v[134:137], v[198:201], v[46:49]
	v_mfma_f32_16x16x32_bf16 v[38:41], v[142:145], v[198:201], v[38:41]
	v_mfma_f32_16x16x32_bf16 v[30:33], v[134:137], v[206:209], v[30:33]
	v_mfma_f32_16x16x32_bf16 v[22:25], v[142:145], v[206:209], v[22:25]
	v_mfma_f32_16x16x32_bf16 v[14:17], v[134:137], v[222:225], v[14:17]
	v_mfma_f32_16x16x32_bf16 v[6:9], v[142:145], v[222:225], v[6:9]
	v_mfma_f32_16x16x32_bf16 v[58:61], v[146:149], v[186:189], v[58:61]
	v_mfma_f32_16x16x32_bf16 v[50:53], v[154:157], v[186:189], v[50:53]
	v_mfma_f32_16x16x32_bf16 v[42:45], v[146:149], v[194:197], v[42:45]
	v_mfma_f32_16x16x32_bf16 v[34:37], v[154:157], v[194:197], v[34:37]
	v_mfma_f32_16x16x32_bf16 v[26:29], v[146:149], v[202:205], v[26:29]
	v_mfma_f32_16x16x32_bf16 v[18:21], v[154:157], v[202:205], v[18:21]
	v_mfma_f32_16x16x32_bf16 v[10:13], v[146:149], v[218:221], v[10:13]
	v_mfma_f32_16x16x32_bf16 v[2:5], v[154:157], v[218:221], v[2:5]
	v_mfma_f32_16x16x32_bf16 v[58:61], v[150:153], v[190:193], v[58:61]
	v_mfma_f32_16x16x32_bf16 v[50:53], v[182:185], v[190:193], v[50:53]
	v_mfma_f32_16x16x32_bf16 v[42:45], v[150:153], v[198:201], v[42:45]
	v_mfma_f32_16x16x32_bf16 v[34:37], v[182:185], v[198:201], v[34:37]
	v_mfma_f32_16x16x32_bf16 v[26:29], v[150:153], v[206:209], v[26:29]
	v_mfma_f32_16x16x32_bf16 v[18:21], v[182:185], v[206:209], v[18:21]
	v_mfma_f32_16x16x32_bf16 v[10:13], v[150:153], v[222:225], v[10:13]
	v_mfma_f32_16x16x32_bf16 v[2:5], v[182:185], v[222:225], v[2:5]
	s_setprio 0
	s_barrier
	ds_read_b128 v[130:133], v228
	ds_read_b128 v[134:137], v228 offset:1024
	ds_read_b128 v[138:141], v228 offset:2048
	ds_read_b128 v[142:145], v228 offset:3072
	ds_read_b128 v[146:149], v229
	ds_read_b128 v[150:153], v229 offset:1024
	ds_read_b128 v[154:157], v229 offset:2048
	ds_read_b128 v[182:185], v229 offset:3072
	s_add_u32 s2, s2, s50
	s_addc_u32 s3, s3, s51
	s_mov_b32 m0, s92
	ds_read_b128 v[186:189], v217 offset:32768
	ds_read_b128 v[190:193], v217 offset:33792
	ds_read_b128 v[194:197], v217 offset:34816
	ds_read_b128 v[198:201], v217 offset:35840
	ds_read_b128 v[202:205], v217 offset:36864
	ds_read_b128 v[206:209], v217 offset:37888
	ds_read_b128 v[218:221], v217 offset:38912
	ds_read_b128 v[222:225], v217 offset:39936
	global_load_lds_dwordx4 v158, s[2:3]
	s_mov_b32 m0, s93
	s_nop 0
	global_load_lds_dwordx4 v162, s[2:3]
	s_waitcnt vmcnt(8)
	s_waitcnt lgkmcnt(0)
	s_barrier
; #define PG8_STAGE(bufoff, gbase, voff) do { _Pragma("unroll") for (int _i = 0; _i < 2; ++_i) \
;         __builtin_amdgcn_global_load_lds((const unsigned*)((const char*)(gbase) + (voff)[_i]), (LAS unsigned*)(lds + (bufoff) + ldsw + _i * 8192), 16, 0, 0); } while (0)
; #define PG8_LDA(dst, b, h) do { _Pragma("unroll") for (int m = 0; m < 4; ++m) _Pragma("unroll") for (int k = 0; k < 2; ++k) dst[m][k] = *(const LAS bf16x8*)(lds + PG8_SA(b, h) + aoff + m * 2048 + k * 1024); } while (0)
; #define PG8_MMA(ai, bj, At, Bt) do { __builtin_amdgcn_s_setprio(1); _Pragma("unroll") for (int m = 0; m < 4; ++m) _Pragma("unroll") for (int n = 0; n < 2; ++n) _Pragma("unroll") for (int k = 0; k < 2; ++k) \
;         acc[ai][bj][m][n] = __builtin_amdgcn_mfma_f32_16x16x32_bf16(Bt[n][k], At[m][k], acc[ai][bj][m][n], 0, 0, 0); __builtin_amdgcn_s_setprio(0); } while (0)
; #define PG8_WAIT_V(n) asm volatile("s_waitcnt vmcnt(" #n ")" ::: "memory")
; #define PG8_WAIT_L(n) asm volatile("s_waitcnt lgkmcnt(" #n ")" ::: "memory")
; #define PG8_BAR __builtin_amdgcn_s_barrier()
; #define PG8_SCHED __builtin_amdgcn_sched_barrier(0)
; __device__ __forceinline__ void gemm_phase(LAS unsigned char* lds, const Gemm g, const StaticOrder& S, const Epi& E) {
;     ...
;             PG8_WAIT_V(8); PG8_WAIT_L(0); PG8_BAR; PG8_MMA(0, 0, At, B0); PG8_MMA(0, 1, At, B1); PG8_BAR; PG8_SCHED;
;             PG8_LDA(At, 1, 1); PG8_STAGE(PG8_SB(1, 0), b3, voffB); PG8_STAGE(PG8_SB(1, 1), b3 + hstepB, voffB); PG8_STAGE(PG8_SA(1, 0), a3, voffA);
;             PG8_WAIT_V(8); PG8_WAIT_L(0); PG8_BAR; PG8_MMA(1, 0, At, B0); PG8_MMA(1, 1, At, B1); PG8_BAR; PG8_SCHED;
;         }
	s_setprio 1
	v_mfma_f32_16x16x32_bf16 v[114:117], v[130:133], v[186:189], v[114:117]
	v_mfma_f32_16x16x32_bf16 v[126:129], v[138:141], v[186:189], v[126:129]
	v_mfma_f32_16x16x32_bf16 v[110:113], v[130:133], v[194:197], v[110:113]
	v_mfma_f32_16x16x32_bf16 v[102:105], v[138:141], v[194:197], v[102:105]
	v_mfma_f32_16x16x32_bf16 v[94:97], v[130:133], v[202:205], v[94:97]
	v_mfma_f32_16x16x32_bf16 v[86:89], v[138:141], v[202:205], v[86:89]
	v_mfma_f32_16x16x32_bf16 v[78:81], v[130:133], v[218:221], v[78:81]
	v_mfma_f32_16x16x32_bf16 v[70:73], v[138:141], v[218:221], v[70:73]
	v_mfma_f32_16x16x32_bf16 v[114:117], v[134:137], v[190:193], v[114:117]
	v_mfma_f32_16x16x32_bf16 v[126:129], v[142:145], v[190:193], v[126:129]
	v_mfma_f32_16x16x32_bf16 v[110:113], v[134:137], v[198:201], v[110:113]
	v_mfma_f32_16x16x32_bf16 v[102:105], v[142:145], v[198:201], v[102:105]
	v_mfma_f32_16x16x32_bf16 v[94:97], v[134:137], v[206:209], v[94:97]
	v_mfma_f32_16x16x32_bf16 v[86:89], v[142:145], v[206:209], v[86:89]
	v_mfma_f32_16x16x32_bf16 v[78:81], v[134:137], v[222:225], v[78:81]
	v_mfma_f32_16x16x32_bf16 v[70:73], v[142:145], v[222:225], v[70:73]
	v_mfma_f32_16x16x32_bf16 v[122:125], v[146:149], v[186:189], v[122:125]
	v_mfma_f32_16x16x32_bf16 v[118:121], v[154:157], v[186:189], v[118:121]
	v_mfma_f32_16x16x32_bf16 v[106:109], v[146:149], v[194:197], v[106:109]
	v_mfma_f32_16x16x32_bf16 v[98:101], v[154:157], v[194:197], v[98:101]
	v_mfma_f32_16x16x32_bf16 v[90:93], v[146:149], v[202:205], v[90:93]
	v_mfma_f32_16x16x32_bf16 v[82:85], v[154:157], v[202:205], v[82:85]
	v_mfma_f32_16x16x32_bf16 v[74:77], v[146:149], v[218:221], v[74:77]
	v_mfma_f32_16x16x32_bf16 v[66:69], v[154:157], v[218:221], v[66:69]
	v_mfma_f32_16x16x32_bf16 v[122:125], v[150:153], v[190:193], v[122:125]
	v_mfma_f32_16x16x32_bf16 v[118:121], v[182:185], v[190:193], v[118:121]
	v_mfma_f32_16x16x32_bf16 v[106:109], v[150:153], v[198:201], v[106:109]
	v_mfma_f32_16x16x32_bf16 v[98:101], v[182:185], v[198:201], v[98:101]
	v_mfma_f32_16x16x32_bf16 v[90:93], v[150:153], v[206:209], v[90:93]
	v_mfma_f32_16x16x32_bf16 v[82:85], v[182:185], v[206:209], v[82:85]
	v_mfma_f32_16x16x32_bf16 v[74:77], v[150:153], v[222:225], v[74:77]
	v_mfma_f32_16x16x32_bf16 v[66:69], v[182:185], v[222:225], v[66:69]
	s_setprio 0
	s_barrier
	s_add_u32 s40, s40, 0x80
	s_addc_u32 s41, s41, 0
	s_sub_u32 s100, s40, s52
	s_subb_u32 s101, s41, s53
	s_sub_u32 s2, s2, s50
	s_subb_u32 s3, s3, s51
	s_add_u32 s2, s2, 0x80
	s_addc_u32 s3, s3, 0
	s_add_i32 vcc_lo, s25, s70
	s_mov_b32 m0, vcc_lo
	ds_read_b128 v[186:189], v217 offset:49152
	ds_read_b128 v[190:193], v217 offset:50176
	ds_read_b128 v[194:197], v217 offset:51200
	ds_read_b128 v[198:201], v217 offset:52224
	ds_read_b128 v[202:205], v217 offset:53248
	ds_read_b128 v[206:209], v217 offset:54272
	ds_read_b128 v[218:221], v217 offset:55296
	ds_read_b128 v[222:225], v217 offset:56320
	global_load_lds_dwordx4 v160, s[100:101]
	s_add_i32 m0, vcc_lo, 0x2000
	s_add_i32 vcc_lo, s26, s70
	global_load_lds_dwordx4 v164, s[100:101]
	s_mov_b32 m0, vcc_lo
	s_nop 0
	global_load_lds_dwordx4 v160, s[40:41]
	s_add_i32 m0, vcc_lo, 0x2000
	s_nop 0
	global_load_lds_dwordx4 v164, s[40:41]
	s_mov_b32 m0, s58
	s_nop 0
	global_load_lds_dwordx4 v158, s[2:3]
	s_mov_b32 m0, s59
	s_nop 0
	global_load_lds_dwordx4 v162, s[2:3]
	s_waitcnt vmcnt(8)
	s_waitcnt lgkmcnt(0)
	s_barrier
	s_setprio 1
	v_mfma_f32_16x16x32_bf16 v[62:65], v[130:133], v[186:189], v[62:65]
	v_mfma_f32_16x16x32_bf16 v[54:57], v[138:141], v[186:189], v[54:57]
	v_mfma_f32_16x16x32_bf16 v[46:49], v[130:133], v[194:197], v[46:49]
	v_mfma_f32_16x16x32_bf16 v[38:41], v[138:141], v[194:197], v[38:41]
	v_mfma_f32_16x16x32_bf16 v[30:33], v[130:133], v[202:205], v[30:33]
	v_mfma_f32_16x16x32_bf16 v[22:25], v[138:141], v[202:205], v[22:25]
	v_mfma_f32_16x16x32_bf16 v[14:17], v[130:133], v[218:221], v[14:17]
	v_mfma_f32_16x16x32_bf16 v[6:9], v[138:141], v[218:221], v[6:9]
	v_mfma_f32_16x16x32_bf16 v[62:65], v[134:137], v[190:193], v[62:65]
	v_mfma_f32_16x16x32_bf16 v[54:57], v[142:145], v[190:193], v[54:57]
	v_mfma_f32_16x16x32_bf16 v[46:49], v[134:137], v[198:201], v[46:49]
	v_mfma_f32_16x16x32_bf16 v[38:41], v[142:145], v[198:201], v[38:41]
	v_mfma_f32_16x16x32_bf16 v[30:33], v[134:137], v[206:209], v[30:33]
	v_mfma_f32_16x16x32_bf16 v[22:25], v[142:145], v[206:209], v[22:25]
	v_mfma_f32_16x16x32_bf16 v[14:17], v[134:137], v[222:225], v[14:17]
	v_mfma_f32_16x16x32_bf16 v[6:9], v[142:145], v[222:225], v[6:9]
	v_mfma_f32_16x16x32_bf16 v[58:61], v[146:149], v[186:189], v[58:61]
	v_mfma_f32_16x16x32_bf16 v[50:53], v[154:157], v[186:189], v[50:53]
	v_mfma_f32_16x16x32_bf16 v[42:45], v[146:149], v[194:197], v[42:45]
	v_mfma_f32_16x16x32_bf16 v[34:37], v[154:157], v[194:197], v[34:37]
	v_mfma_f32_16x16x32_bf16 v[26:29], v[146:149], v[202:205], v[26:29]
	v_mfma_f32_16x16x32_bf16 v[18:21], v[154:157], v[202:205], v[18:21]
	v_mfma_f32_16x16x32_bf16 v[10:13], v[146:149], v[218:221], v[10:13]
	v_mfma_f32_16x16x32_bf16 v[2:5], v[154:157], v[218:221], v[2:5]
	v_mfma_f32_16x16x32_bf16 v[58:61], v[150:153], v[190:193], v[58:61]
	v_mfma_f32_16x16x32_bf16 v[50:53], v[182:185], v[190:193], v[50:53]
	v_mfma_f32_16x16x32_bf16 v[42:45], v[150:153], v[198:201], v[42:45]
	v_mfma_f32_16x16x32_bf16 v[34:37], v[182:185], v[198:201], v[34:37]
	v_mfma_f32_16x16x32_bf16 v[26:29], v[150:153], v[206:209], v[26:29]
	v_mfma_f32_16x16x32_bf16 v[18:21], v[182:185], v[206:209], v[18:21]
	v_mfma_f32_16x16x32_bf16 v[10:13], v[150:153], v[222:225], v[10:13]
	v_mfma_f32_16x16x32_bf16 v[2:5], v[182:185], v[222:225], v[2:5]
	s_setprio 0
	s_barrier
	s_add_u32 s0, s0, 0x100
	s_addc_u32 s1, s1, 0
	s_add_u32 s5, s5, 0x100
	s_addc_u32 s16, s16, 0
	s_cmp_ge_i32 s27, s84
	s_mov_b32 s17, s27
	s_cbranch_scc0 .LBB0_177
	s_and_b64 vcc, exec, s[74:75]
	s_cbranch_vccz .LBB0_180
